# static priority raise strategy: one s_setprio 1 for waves 4-7 on entry to the SSD chunk loop path, reset at the C-D barrier
# speedup vs baseline: 1.0033x; 1.0033x over previous
; __device__ __forceinline__ int lane_fresh() { int l; asm volatile("v_mbcnt_lo_u32_b32 %0, -1, 0\n\tv_mbcnt_hi_u32_b32 %0, -1, %0" : "=v"(l)); return l; }
; __device__ __forceinline__ void ssd_prompt_item(const Params& p, int item, const int wv) {
;   const int lane = lane_fresh(), wid = wv, tid = wv * 64 + lane, fr = lane & 15, fq = lane >> 4;
;   const int h = item & 15, b = item >> 4, g = h >> 3;
;   char* ws = p.ws;
;   u16* C_l = (u16*)g_shm;
;   u16* B_l = C_l + 128 * 136;
;   u16* G_l = B_l;
;   u16* BT_l = B_l + 128 * 136;
;   u16* xT_l = BT_l + 128 * 136;
;   u16* xw_l = xT_l + 64 * 136;
;   u16* h_l = xw_l + 64 * 136;
;   float* acum_l = (float*)(h_l + 64 * 136);
;   float* dt_l = acum_l + 128;
;   const u16* XBC = (const u16*)(ws + OFF_XBC);
;   const u16* ZS = (const u16*)(ws + OFF_ZS);
;   const float* DT = (const float*)(ws + OFF_DT);
;   u16* Y = (u16*)((char*)p.out + OOFF_XN);
;   float* YPS = (float*)(ws + OFF_YPS);
;   const float Ah = -__expf(p.in[16][h]);
;   const float Dh = p.in[17][h];
;   const float* convw = p.in[13];
;   const float* convb = p.in[14];
;   const int cc = tid & 31, rg = tid >> 5;
;   const int colbc = (cc < 16) ? (1024 + g * 128 + cc * 8) : (1280 + g * 128 + (cc - 16) * 8);
;   const int xc = tid & 7, xr = tid >> 3;
;   const int colx = h * 64 + xc * 8;
;   const int j0 = rg * 8;
;   f32x4 hacc[4];
; #pragma unroll
;   for (int pb = 0; pb < 4; ++pb) hacc[pb] = (f32x4){0.f, 0.f, 0.f, 0.f};
;   u32x4 u[11], ux[5];
;   float a0 = 0.f, a1 = 0.f;
;     ...
;   SSD_PREFETCH(0);
; __device__ __forceinline__ void phaseC(const Params& p, const int wv, const int r0, const int r1, const int r2, const int r3, const int r4, unsigned* bar) {
;   const int wid = wv;
;   const int nS = gridDim.x >> 1;
;   if ((int)blockIdx.x < nS) {
;     for (int it = blockIdx.x; it < 128 * r0; it += nS) ssd_prompt_item(p, it & 127, wv);
.LBB0_562:
	s_and_b64 vcc, exec, s[0:1]
	s_cbranch_vccz .LBB0_633
	s_lshl_b32 s1, s56, 7
	v_readlane_b32 s0, v251, 0
	s_cmp_ge_i32 s0, s1
	v_writelane_b32 v250, s1, 4
	s_cbranch_scc1 .LBB0_633
	s_cmp_ge_u32 s83, 4
	s_cbranch_scc0 .Lprio_c
	s_setprio 1
.Lprio_c:
	s_lshl_b32 s0, s83, 5
	s_add_i32 s0, s0, 16
	s_add_i32 s0, s0, 0x22000
	s_lshl_b32 s4, s83, 4
	s_cmpk_gt_u32 s81, 0x7f
	s_cselect_b64 s[2:3], -1, 0
	s_cmpk_gt_u32 s81, 0xbf
	s_cselect_b64 s[14:15], -1, 0
	s_cmpk_gt_u32 s81, 0xff
	s_cselect_b64 s[16:17], -1, 0
	s_cmpk_gt_u32 s81, 0x13f
	s_cselect_b64 s[26:27], -1, 0
	s_cmpk_gt_u32 s81, 0x17f
	s_cselect_b64 s[28:29], -1, 0
	s_cmpk_gt_u32 s81, 0x1bf
	v_writelane_b32 v250, s0, 5
	s_cselect_b64 s[30:31], -1, 0
	s_lshl_b32 s0, s83, 6
	s_add_u32 s0, s48, s0
	s_addc_u32 s1, s49, 0
	s_add_u32 s0, s0, 0x48a4000
	s_addc_u32 s1, s1, 0
	v_writelane_b32 v250, s0, 6
	s_mov_b32 s5, 0
	v_mov_b32_e32 v143, 0
	v_writelane_b32 v250, s1, 7
	s_add_u32 s0, s50, 0x72ae000
	s_addc_u32 s1, s51, 0
	v_writelane_b32 v250, s0, 8
	s_movk_i32 s33, 0xc00
	s_mov_b32 s38, 0xffff0000
	v_writelane_b32 v250, s1, 9
	s_add_u32 s0, s50, 0x2e20000
	s_addc_u32 s1, s51, 0
	v_writelane_b32 v250, s0, 10
	s_mov_b64 s[34:35], 0x60000
	s_mov_b64 s[36:37], 0x40000
	v_writelane_b32 v250, s1, 11
	s_add_u32 s0, s48, 64
	s_addc_u32 s1, s49, 0
	v_writelane_b32 v250, s0, 12
	s_add_i32 s39, 16, 0x265fc
	v_bfrev_b32_e32 v161, 0.5
	v_writelane_b32 v250, s1, 13
	s_add_i32 s0, 16, 0x19800
	v_writelane_b32 v250, s0, 14
	s_add_i32 s0, 16, 0x1dc00
	v_writelane_b32 v250, s0, 15
	s_add_i32 s0, 16, 0x26400
	v_writelane_b32 v250, s0, 16
	s_add_i32 s0, 16, 0x26600
	v_writelane_b32 v250, s0, 17
	s_add_i32 s0, 16, 0x11000
	v_writelane_b32 v250, s0, 18
	v_writelane_b32 v250, s4, 19
	s_lshl_b32 s4, s4, 2
	v_readlane_b32 s0, v251, 0
	v_writelane_b32 v250, s4, 20
	s_mov_b32 s40, s0
	s_mov_b32 s44, s0
	s_mov_b32 s45, s0
	s_mov_b32 s68, s0
	v_writelane_b32 v250, s5, 21
	s_branch .LBB0_566

; __device__ __forceinline__ int lane_fresh() { int l; asm volatile("v_mbcnt_lo_u32_b32 %0, -1, 0\n\tv_mbcnt_hi_u32_b32 %0, -1, %0" : "=v"(l)); return l; }
; #define LAS __attribute__((address_space(3)))
; __device__ __forceinline__ unsigned xb_xcc_id() { return (unsigned)__builtin_amdgcn_s_getreg((3 << 11) | 20) & 0xFu; }
; #define RB(bit) ({ int n_ = (REP & (1 << bit)) ? 2 : 1; asm volatile("" : "+s"(n_)); n_; })
; __device__ __forceinline__ void xcd_barrier(unsigned* bar, const int wv) {
;   asm volatile("s_waitcnt vmcnt(0)" ::: "memory");
;   __syncthreads();
;   if (wv == 0) {
;     if (lane_fresh() == 0) {
;       volatile LAS unsigned* st = (volatile LAS unsigned*)&xb_words;
;       const unsigned x = xb_xcc_id();
;       __builtin_amdgcn_s_waitcnt(0);
;       unsigned nloc = st[0], nx = st[1];
;       if (nloc == 0u) { xcd_barrier_complete(bar, x, nloc, nx); st[0] = nloc; st[1] = nx; }
; __global__ void __launch_bounds__(NTHREADS) fwd_megakernel(Params p) {
;     ...
;   phaseC(p, wv, RB(8), RB(9), RB(10), RB(11), RB(12), bar);
;   xcd_barrier(bar, wv);
.LBB0_633:
	s_setprio 0
	s_waitcnt vmcnt(0)
	v_readlane_b32 s0, v251, 58
	v_readlane_b32 s1, v251, 59
	s_and_b64 vcc, exec, s[0:1]
	s_mov_b32 s33, 1
	s_waitcnt lgkmcnt(0)
	s_barrier
	s_cbranch_vccnz .LBB0_687
	v_mbcnt_lo_u32_b32 v0, -1, 0
	v_mbcnt_hi_u32_b32 v0, -1, v0
	s_nop 0
	v_cmp_eq_u32_e32 vcc, 0, v0
	s_and_saveexec_b64 s[0:1], vcc
	s_cbranch_execz .LBB0_686
	v_mov_b32_e32 v0, 0
	s_getreg_b32 s2, hwreg(HW_REG_XCC_ID, 0, 4)
	s_waitcnt vmcnt(0) expcnt(0) lgkmcnt(0)
	ds_read_b32 v2, v0
	ds_read_b32 v1, v0 offset:4
	s_and_b32 s44, s2, 15
	s_waitcnt lgkmcnt(1)
	v_cmp_ne_u32_e32 vcc, 0, v2
	s_cbranch_vccnz .LBB0_650
	s_add_u32 s2, s50, 0x12416200
	s_addc_u32 s3, s51, 0
	s_add_u32 s4, s50, 0x12416400
	s_addc_u32 s5, s51, 0
	s_add_u32 s6, s50, 0x12416500
	s_addc_u32 s7, s51, 0
	s_add_u32 s8, s50, 0x12416600
	s_addc_u32 s9, s51, 0
	s_add_u32 s10, s50, 0x12416700
	s_addc_u32 s11, s51, 0
	s_add_u32 s12, s50, 0x12416800
	s_addc_u32 s13, s51, 0
	s_add_u32 s14, s50, 0x12416900
	s_addc_u32 s15, s51, 0
	s_add_u32 s16, s50, 0x12416a00
	s_addc_u32 s17, s51, 0
	s_add_u32 s18, s50, 0x12416b00
	s_addc_u32 s19, s51, 0
	s_add_u32 s20, s50, 0x12416c00
	s_addc_u32 s21, s51, 0
	s_add_u32 s22, s50, 0x12416d00
	s_addc_u32 s23, s51, 0
	s_add_u32 s24, s50, 0x12416e00
	s_addc_u32 s25, s51, 0
	s_add_u32 s26, s50, 0x12416f00
	s_addc_u32 s27, s51, 0
	s_add_u32 s28, s50, 0x12417000
	s_addc_u32 s29, s51, 0
	s_add_u32 s30, s50, 0x12417100
	s_addc_u32 s31, s51, 0
	s_add_u32 s34, s50, 0x12417200
	s_addc_u32 s35, s51, 0
	s_add_u32 s36, s50, 0x12417300
	s_addc_u32 s37, s51, 0
	s_mov_b32 s45, 1
	s_branch .LBB0_638
